# stack + LN phases: DPP row reductions instead of ds_bpermute butterflies, counted waits at loop heads
# speedup vs baseline: 1.0127x; 1.0080x over previous
; __device__ __forceinline__ float bflo(unsigned w) { return __uint_as_float(w << 16); }
; __device__ __forceinline__ float bfhi(unsigned w) { return __uint_as_float(w & 0xffff0000u); }
; __device__ __forceinline__ void ln_panel_b(bf16_t* hb, float* outf, const float* gam, const float* bet) {
;     ...
;     for (int it = 0; it < 32 / NB; ++it) {
;         const int r = r0 + it * NB;
;         float v[NB][16];
; #pragma unroll
;         for (int b = 0; b < NB; ++b)
; #pragma unroll
;             for (int j = 0; j < 2; ++j)
; #pragma unroll
;                 for (int k = 0; k < 4; ++k) { v[b][8 * j + 2 * k] = bflo(nxt[b][j][k]); v[b][8 * j + 2 * k + 1] = bfhi(nxt[b][j][k]); }
;         if (it + 1 < 32 / NB) {
; #pragma unroll
;             for (int b = 0; b < NB; ++b)
; #pragma unroll
;                 for (int j = 0; j < 2; ++j) nxt[b][j] = ((const u32x4*)(hb + (size_t)(r + NB + b) * DM))[lane + 64 * j];
;         }
;         float s[NB], s2[NB];
; #pragma unroll
;         for (int b = 0; b < NB; ++b) { s[b] = 0.f;
; #pragma unroll
;             for (int k = 0; k < 16; ++k) s[b] += v[b][k]; }
; #pragma unroll
;         for (int o = 1; o < 64; o <<= 1)
; #pragma unroll
;             for (int b = 0; b < NB; ++b) s[b] += __shfl_xor(s[b], o);
; #pragma unroll
;         for (int b = 0; b < NB; ++b) { const float mean = s[b] * (1.f / DM); s2[b] = 0.f;
; #pragma unroll
;             for (int k = 0; k < 16; ++k) { v[b][k] -= mean; s2[b] += v[b][k] * v[b][k]; } }
; #pragma unroll
;         for (int o = 1; o < 64; o <<= 1)
; #pragma unroll
;             for (int b = 0; b < NB; ++b) s2[b] += __shfl_xor(s2[b], o);
.LBB0_425:
	s_waitcnt vmcnt(4)
	v_lshlrev_b32_e32 v0, 16, v34
	v_and_b32_e32 v51, 0xffff0000, v34
	v_add_f32_e32 v86, 0, v0
	v_lshlrev_b32_e32 v56, 16, v35
	v_add_f32_e32 v86, v86, v51
	v_and_b32_e32 v57, 0xffff0000, v35
	v_add_f32_e32 v86, v86, v56
	v_lshlrev_b32_e32 v58, 16, v36
	v_add_f32_e32 v86, v86, v57
	v_and_b32_e32 v59, 0xffff0000, v36
	v_lshlrev_b32_e32 v70, 16, v42
	v_add_f32_e32 v86, v86, v58
	v_lshlrev_b32_e32 v60, 16, v37
	v_and_b32_e32 v71, 0xffff0000, v42
	v_add_f32_e32 v86, v86, v59
	v_add_f32_e32 v87, 0, v70
	v_and_b32_e32 v61, 0xffff0000, v37
	v_lshlrev_b32_e32 v72, 16, v43
	v_add_f32_e32 v86, v86, v60
	v_add_f32_e32 v87, v87, v71
	v_lshlrev_b32_e32 v62, 16, v38
	v_and_b32_e32 v73, 0xffff0000, v43
	v_add_f32_e32 v86, v86, v61
	v_add_f32_e32 v87, v87, v72
	v_and_b32_e32 v63, 0xffff0000, v38
	v_lshlrev_b32_e32 v74, 16, v44
	v_add_f32_e32 v86, v86, v62
	v_add_f32_e32 v87, v87, v73
	v_lshlrev_b32_e32 v64, 16, v39
	v_and_b32_e32 v75, 0xffff0000, v44
	v_add_f32_e32 v86, v86, v63
	v_add_f32_e32 v87, v87, v74
	v_and_b32_e32 v65, 0xffff0000, v39
	v_lshlrev_b32_e32 v76, 16, v45
	v_add_f32_e32 v86, v86, v64
	v_add_f32_e32 v87, v87, v75
	v_lshlrev_b32_e32 v66, 16, v40
	v_and_b32_e32 v77, 0xffff0000, v45
	v_add_f32_e32 v86, v86, v65
	v_add_f32_e32 v87, v87, v76
	v_and_b32_e32 v67, 0xffff0000, v40
	v_lshlrev_b32_e32 v78, 16, v46
	v_add_f32_e32 v86, v86, v66
	v_add_f32_e32 v87, v87, v77
	v_lshlrev_b32_e32 v68, 16, v41
	v_and_b32_e32 v79, 0xffff0000, v46
	v_add_f32_e32 v86, v86, v67
	v_add_f32_e32 v87, v87, v78
	v_and_b32_e32 v69, 0xffff0000, v41
	v_lshlrev_b32_e32 v80, 16, v47
	v_add_f32_e32 v86, v86, v68
	v_add_f32_e32 v87, v87, v79
	v_and_b32_e32 v81, 0xffff0000, v47
	v_add_f32_e32 v86, v86, v69
	v_add_f32_e32 v87, v87, v80
	v_lshlrev_b32_e32 v82, 16, v48
	v_add_f32_e32 v87, v87, v81
	v_and_b32_e32 v83, 0xffff0000, v48
	v_add_f32_e32 v87, v87, v82
	v_lshlrev_b32_e32 v84, 16, v49
	v_add_f32_e32 v87, v87, v83
	v_and_b32_e32 v85, 0xffff0000, v49
	v_add_f32_e32 v87, v87, v84
	v_add_f32_e32 v87, v87, v85
	s_waitcnt lgkmcnt(0)
	s_nop 1
	v_add_f32_dpp v86, v86, v86 quad_perm:[1,0,3,2] row_mask:0xf bank_mask:0xf
	v_lshl_add_u64 v[54:55], v[52:53], 0, s[26:27]
	s_mov_b32 s1, 0x6001000
	v_add_co_u32_e32 v46, vcc, s1, v54
	s_waitcnt lgkmcnt(0)
	s_nop 1
	v_add_f32_dpp v87, v87, v87 quad_perm:[1,0,3,2] row_mask:0xf bank_mask:0xf
	v_addc_co_u32_e32 v47, vcc, 0, v55, vcc
	global_load_dwordx4 v[34:37], v[46:47], off
	global_load_dwordx4 v[38:41], v[46:47], off offset:1024
	global_load_dwordx4 v[42:45], v[46:47], off offset:2048
	s_nop 0
	global_load_dwordx4 v[46:49], v[46:47], off offset:3072
	s_mov_b32 s1, 0x6000000
	s_waitcnt lgkmcnt(0)
	s_nop 1
	v_add_f32_dpp v86, v86, v86 quad_perm:[2,3,0,1] row_mask:0xf bank_mask:0xf
	s_add_u32 s26, s26, 0x1000
	s_addc_u32 s27, s27, 0
	s_cmpk_lg_u32 s26, 0xf000
	s_waitcnt lgkmcnt(0)
	s_nop 1
	v_add_f32_dpp v87, v87, v87 quad_perm:[2,3,0,1] row_mask:0xf bank_mask:0xf
	s_waitcnt lgkmcnt(0)
	s_nop 1
	v_add_f32_dpp v86, v86, v86 row_half_mirror row_mask:0xf bank_mask:0xf
	s_waitcnt lgkmcnt(0)
	s_nop 1
	v_add_f32_dpp v87, v87, v87 row_half_mirror row_mask:0xf bank_mask:0xf
	s_waitcnt lgkmcnt(0)
	s_nop 1
	v_add_f32_dpp v86, v86, v86 row_mirror row_mask:0xf bank_mask:0xf
	s_waitcnt lgkmcnt(0)
	s_nop 1
	v_add_f32_dpp v87, v87, v87 row_mirror row_mask:0xf bank_mask:0xf
	s_waitcnt lgkmcnt(0)
	s_waitcnt lgkmcnt(0)
	s_waitcnt lgkmcnt(0)
	s_nop 0
	v_readlane_b32 s98, v86, 0
	v_readlane_b32 s99, v86, 16
	v_readlane_b32 s100, v86, 32
	v_readlane_b32 s101, v86, 48
	v_mov_b32_e32 v86, s98
	v_add_f32_e32 v86, s99, v86
	v_mov_b32_e32 v88, s100
	v_add_f32_e32 v88, s101, v88
	v_add_f32_e32 v86, v86, v88
	v_fmac_f32_e32 v51, 0xba800000, v86
	v_fmac_f32_e32 v0, 0xba800000, v86
	v_fmac_f32_e32 v56, 0xba800000, v86
	v_fmac_f32_e32 v57, 0xba800000, v86
	s_waitcnt lgkmcnt(0)
	s_nop 0
	v_readlane_b32 s98, v87, 0
	v_readlane_b32 s99, v87, 16
	v_readlane_b32 s100, v87, 32
	v_readlane_b32 s101, v87, 48
	v_mov_b32_e32 v87, s98
	v_add_f32_e32 v87, s99, v87
	v_mov_b32_e32 v88, s100
	v_add_f32_e32 v88, s101, v88
	v_add_f32_e32 v87, v87, v88
	v_mul_f32_e32 v88, v51, v51
	v_fmac_f32_e32 v88, v0, v0
	v_fmac_f32_e32 v88, v56, v56
	v_fmac_f32_e32 v88, v57, v57
	v_fmac_f32_e32 v58, 0xba800000, v86
	v_fmac_f32_e32 v88, v58, v58
	v_fmac_f32_e32 v59, 0xba800000, v86
	v_fmac_f32_e32 v71, 0xba800000, v87
	v_fmac_f32_e32 v88, v59, v59
	v_fmac_f32_e32 v60, 0xba800000, v86
	v_fmac_f32_e32 v61, 0xba800000, v86
	v_fmac_f32_e32 v62, 0xba800000, v86
	v_fmac_f32_e32 v63, 0xba800000, v86
	v_fmac_f32_e32 v64, 0xba800000, v86
	v_fmac_f32_e32 v65, 0xba800000, v86
	v_fmac_f32_e32 v66, 0xba800000, v86
	v_fmac_f32_e32 v67, 0xba800000, v86
	v_fmac_f32_e32 v68, 0xba800000, v86
	v_fmac_f32_e32 v69, 0xba800000, v86
	v_fmac_f32_e32 v70, 0xba800000, v87
	v_mul_f32_e32 v86, v71, v71
	v_fmac_f32_e32 v88, v60, v60
	v_fmac_f32_e32 v86, v70, v70
	v_fmac_f32_e32 v72, 0xba800000, v87
	v_fmac_f32_e32 v88, v61, v61
	v_fmac_f32_e32 v86, v72, v72
	v_fmac_f32_e32 v73, 0xba800000, v87
	v_fmac_f32_e32 v88, v62, v62
	v_fmac_f32_e32 v86, v73, v73
	v_fmac_f32_e32 v74, 0xba800000, v87
	v_fmac_f32_e32 v88, v63, v63
	v_fmac_f32_e32 v86, v74, v74
	v_fmac_f32_e32 v75, 0xba800000, v87
	v_fmac_f32_e32 v88, v64, v64
	v_fmac_f32_e32 v86, v75, v75
	v_fmac_f32_e32 v76, 0xba800000, v87
	v_fmac_f32_e32 v88, v65, v65
	v_fmac_f32_e32 v86, v76, v76
	v_fmac_f32_e32 v77, 0xba800000, v87
	v_fmac_f32_e32 v88, v66, v66
	v_fmac_f32_e32 v86, v77, v77
	v_fmac_f32_e32 v78, 0xba800000, v87
	v_fmac_f32_e32 v88, v67, v67
	v_fmac_f32_e32 v86, v78, v78
	v_fmac_f32_e32 v79, 0xba800000, v87
	v_fmac_f32_e32 v88, v68, v68
	v_fmac_f32_e32 v86, v79, v79
	v_fmac_f32_e32 v80, 0xba800000, v87
	v_fmac_f32_e32 v88, v69, v69
	v_fmac_f32_e32 v86, v80, v80
	v_fmac_f32_e32 v81, 0xba800000, v87
	v_fmac_f32_e32 v86, v81, v81
	v_fmac_f32_e32 v82, 0xba800000, v87
	v_fmac_f32_e32 v83, 0xba800000, v87
	v_fmac_f32_e32 v84, 0xba800000, v87
	v_fmac_f32_e32 v85, 0xba800000, v87
	v_fmac_f32_e32 v86, v82, v82
	v_fmac_f32_e32 v86, v83, v83
	v_fmac_f32_e32 v86, v84, v84
	v_fmac_f32_e32 v86, v85, v85
	s_waitcnt lgkmcnt(0)
; __device__ __forceinline__ unsigned pk2(float lo, float hi) { unsigned r; asm("v_cvt_pk_bf16_f32 %0, %1, %2" : "=v"(r) : "v"(lo), "v"(hi)); return r; }
; __device__ __forceinline__ void ln_panel_b(bf16_t* hb, float* outf, const float* gam, const float* bet) {
;     ...
;         for (int o = 1; o < 64; o <<= 1)
; #pragma unroll
;             for (int b = 0; b < NB; ++b) s2[b] += __shfl_xor(s2[b], o);
; #pragma unroll
;         for (int b = 0; b < NB; ++b) {
;             const float rstd = 1.f / sqrtf(s2[b] * (1.f / DM) + LN_EPS);
; #pragma unroll
;             for (int j = 0; j < 2; ++j) {
;                 float o[8];
; #pragma unroll
;                 for (int k = 0; k < 8; ++k) o[k] = v[b][8 * j + k] * rstd * gv[j][k >> 2][k & 3] + bv[j][k >> 2][k & 3];
;                 if (outf) { f32x4* op = (f32x4*)(outf + (size_t)(r + b) * DM + 512 * j + 8 * lane); op[0] = (f32x4){o[0], o[1], o[2], o[3]}; op[1] = (f32x4){o[4], o[5], o[6], o[7]}; }
;                 else { u32x4 w; w.x = pk2(o[0], o[1]); w.y = pk2(o[2], o[3]); w.z = pk2(o[4], o[5]); w.w = pk2(o[6], o[7]); ((u32x4*)(hb + (size_t)(r + b) * DM))[lane + 64 * j] = w; }
;             }
	s_nop 1
	v_add_f32_dpp v87, v88, v88 quad_perm:[1,0,3,2] row_mask:0xf bank_mask:0xf
	s_waitcnt lgkmcnt(0)
	s_nop 1
	v_add_f32_dpp v86, v86, v86 quad_perm:[1,0,3,2] row_mask:0xf bank_mask:0xf
	s_waitcnt lgkmcnt(0)
	s_nop 1
	v_add_f32_dpp v87, v87, v87 quad_perm:[2,3,0,1] row_mask:0xf bank_mask:0xf
	s_waitcnt lgkmcnt(0)
	s_nop 1
	v_add_f32_dpp v86, v86, v86 quad_perm:[2,3,0,1] row_mask:0xf bank_mask:0xf
	s_waitcnt lgkmcnt(0)
	s_nop 1
	v_add_f32_dpp v87, v87, v87 row_half_mirror row_mask:0xf bank_mask:0xf
	s_waitcnt lgkmcnt(0)
	s_nop 1
	v_add_f32_dpp v86, v86, v86 row_half_mirror row_mask:0xf bank_mask:0xf
	s_waitcnt lgkmcnt(0)
	s_nop 1
	v_add_f32_dpp v87, v87, v87 row_mirror row_mask:0xf bank_mask:0xf
	s_waitcnt lgkmcnt(0)
	s_nop 1
	v_add_f32_dpp v86, v86, v86 row_mirror row_mask:0xf bank_mask:0xf
	s_waitcnt lgkmcnt(0)
	s_waitcnt lgkmcnt(0)
	s_waitcnt lgkmcnt(0)
	s_nop 0
	v_readlane_b32 s98, v87, 0
	v_readlane_b32 s99, v87, 16
	v_readlane_b32 s100, v87, 32
	v_readlane_b32 s101, v87, 48
	v_mov_b32_e32 v87, s98
	v_add_f32_e32 v87, s99, v87
	v_mov_b32_e32 v88, s100
	v_add_f32_e32 v88, s101, v88
	v_add_f32_e32 v87, v87, v88
	v_fmamk_f32 v87, v87, 0x3a800000, v231
	v_cmp_gt_f32_e32 vcc, s97, v87
	s_waitcnt lgkmcnt(0)
	s_nop 0
	v_readlane_b32 s98, v86, 0
	v_readlane_b32 s99, v86, 16
	v_readlane_b32 s100, v86, 32
	v_readlane_b32 s101, v86, 48
	v_mov_b32_e32 v86, s98
	v_add_f32_e32 v86, s99, v86
	v_mov_b32_e32 v88, s100
	v_add_f32_e32 v88, s101, v88
	v_add_f32_e32 v86, v86, v88
	v_mul_f32_e32 v88, 0x4f800000, v87
	v_cndmask_b32_e32 v87, v87, v88, vcc
	v_sqrt_f32_e32 v88, v87
	s_nop 0
	v_add_u32_e32 v89, -1, v88
	v_fma_f32 v90, -v89, v88, v87
	v_cmp_ge_f32_e64 s[2:3], 0, v90
	v_add_u32_e32 v90, 1, v88
	s_nop 0
	v_cndmask_b32_e64 v89, v88, v89, s[2:3]
	v_fma_f32 v88, -v90, v88, v87
	v_cmp_lt_f32_e64 s[2:3], 0, v88
	s_nop 1
	v_cndmask_b32_e64 v88, v89, v90, s[2:3]
	v_mul_f32_e32 v89, 0x37800000, v88
	v_cndmask_b32_e32 v88, v88, v89, vcc
	v_cmp_class_f32_e32 vcc, v87, v232
	s_nop 1
	v_cndmask_b32_e32 v87, v88, v87, vcc
	v_div_scale_f32 v88, s[2:3], v87, v87, 1.0
	v_rcp_f32_e32 v89, v88
	s_nop 0
	v_fma_f32 v90, -v88, v89, 1.0
	v_fmac_f32_e32 v89, v90, v89
	v_div_scale_f32 v90, vcc, 1.0, v87, 1.0
	v_mul_f32_e32 v91, v90, v89
	v_fma_f32 v92, -v88, v91, v90
	v_fmac_f32_e32 v91, v92, v89
	v_fma_f32 v88, -v88, v91, v90
	v_div_fmas_f32 v88, v88, v89, v91
	v_div_fixup_f32 v87, v88, v87, 1.0
	v_mul_f32_e32 v56, v56, v87
	v_fma_f32 v88, v32, v56, v24
	v_mul_f32_e32 v56, v57, v87
	v_fma_f32 v57, v33, v56, v25
	v_mul_f32_e32 v56, v58, v87
	v_fma_f32 v58, v26, v56, v18
	v_mul_f32_e32 v56, v59, v87
	v_fma_f32 v59, v27, v56, v19
	v_mul_f32_e32 v56, v60, v87
	v_fma_f32 v60, v28, v56, v20
	v_mul_f32_e32 v56, v61, v87
	v_mul_f32_e32 v0, v0, v87
	v_mul_f32_e32 v51, v51, v87
	v_fma_f32 v61, v29, v56, v21
	v_cvt_pk_bf16_f32 v58, v58, v59
	v_cvt_pk_bf16_f32 v59, v60, v61
	v_add_co_u32_e32 v60, vcc, s1, v54
	v_mul_f32_e32 v54, v64, v87
	v_fma_f32 v0, v30, v0, v22
	v_fma_f32 v51, v31, v51, v23
	v_cvt_pk_bf16_f32 v56, v0, v51
	v_addc_co_u32_e32 v61, vcc, 0, v55, vcc
	v_fma_f32 v55, v16, v54, v8
	v_mul_f32_e32 v54, v65, v87
	v_cvt_pk_bf16_f32 v57, v88, v57
	global_store_dwordx4 v[60:61], v[56:59], off
	v_mul_f32_e32 v0, v62, v87
	v_fma_f32 v0, v14, v0, v6
	v_fma_f32 v56, v17, v54, v9
	v_mul_f32_e32 v54, v66, v87
	v_fma_f32 v57, v10, v54, v2
	v_mul_f32_e32 v54, v67, v87
	v_fma_f32 v58, v11, v54, v3
	v_mul_f32_e32 v54, v68, v87
	v_mul_f32_e32 v51, v63, v87
	v_fma_f32 v59, v12, v54, v4
	v_mul_f32_e32 v54, v69, v87
	v_fma_f32 v51, v15, v51, v7
	v_fma_f32 v62, v13, v54, v5
	v_cvt_pk_bf16_f32 v54, v0, v51
	v_fmamk_f32 v0, v86, 0x3a800000, v231
	v_cmp_gt_f32_e32 vcc, s97, v0
	v_mul_f32_e32 v51, 0x4f800000, v0
	v_cvt_pk_bf16_f32 v55, v55, v56
	v_cvt_pk_bf16_f32 v56, v57, v58
	v_cvt_pk_bf16_f32 v57, v59, v62
	global_store_dwordx4 v[60:61], v[54:57], off offset:1024
	v_cndmask_b32_e32 v0, v0, v51, vcc
	v_sqrt_f32_e32 v51, v0
	s_nop 0
	v_add_u32_e32 v54, -1, v51
	v_fma_f32 v55, -v54, v51, v0
	v_cmp_ge_f32_e64 s[2:3], 0, v55
	v_add_u32_e32 v55, 1, v51
	s_nop 0
	v_cndmask_b32_e64 v54, v51, v54, s[2:3]
	v_fma_f32 v51, -v55, v51, v0
	v_cmp_lt_f32_e64 s[2:3], 0, v51
	s_nop 1
	v_cndmask_b32_e64 v51, v54, v55, s[2:3]
	v_mul_f32_e32 v54, 0x37800000, v51
	v_cndmask_b32_e32 v51, v51, v54, vcc
	v_cmp_class_f32_e32 vcc, v0, v232
	s_nop 1
	v_cndmask_b32_e32 v0, v51, v0, vcc
	v_div_scale_f32 v51, s[2:3], v0, v0, 1.0
	v_rcp_f32_e32 v54, v51
	s_nop 0
	v_fma_f32 v55, -v51, v54, 1.0
	v_fmac_f32_e32 v54, v55, v54
	v_div_scale_f32 v55, vcc, 1.0, v0, 1.0
	v_mul_f32_e32 v56, v55, v54
	v_fma_f32 v57, -v51, v56, v55
	v_fmac_f32_e32 v56, v57, v54
	v_fma_f32 v51, -v51, v56, v55
	v_div_fmas_f32 v51, v51, v54, v56
	v_div_fixup_f32 v0, v51, v0, 1.0
	v_mul_f32_e32 v54, v71, v0
	v_mul_f32_e32 v55, v72, v0
	v_mul_f32_e32 v56, v73, v0
	v_mul_f32_e32 v57, v74, v0
	v_mul_f32_e32 v51, v70, v0
	v_fma_f32 v54, v31, v54, v23
	v_fma_f32 v55, v32, v55, v24
	v_fma_f32 v56, v33, v56, v25
	v_fma_f32 v57, v26, v57, v18
	v_mul_f32_e32 v58, v75, v0
	v_mul_f32_e32 v59, v76, v0
	v_mul_f32_e32 v62, v77, v0
	v_fma_f32 v51, v30, v51, v22
	v_fma_f32 v58, v27, v58, v19
	v_fma_f32 v59, v28, v59, v20
	v_fma_f32 v62, v29, v62, v21
	v_cvt_pk_bf16_f32 v54, v51, v54
	v_cvt_pk_bf16_f32 v55, v55, v56
	v_cvt_pk_bf16_f32 v56, v57, v58
	v_cvt_pk_bf16_f32 v57, v59, v62
	global_store_dwordx4 v[60:61], v[54:57], off offset:2048
	v_mul_f32_e32 v51, v78, v0
	v_mul_f32_e32 v58, v83, v0
	v_mul_f32_e32 v54, v79, v0
	v_mul_f32_e32 v55, v80, v0
	v_mul_f32_e32 v56, v81, v0
	v_mul_f32_e32 v57, v82, v0
	v_fma_f32 v54, v15, v54, v7
	v_fma_f32 v55, v16, v55, v8
	v_fma_f32 v56, v17, v56, v9
	v_fma_f32 v57, v10, v57, v2
	v_mul_f32_e32 v59, v84, v0
	v_mul_f32_e32 v0, v85, v0
	v_fma_f32 v51, v14, v51, v6
	v_fma_f32 v58, v11, v58, v3
	v_fma_f32 v59, v12, v59, v4
	v_fma_f32 v0, v13, v0, v5
	v_cvt_pk_bf16_f32 v54, v51, v54
	v_cvt_pk_bf16_f32 v55, v55, v56
	v_cvt_pk_bf16_f32 v56, v57, v58
	v_cvt_pk_bf16_f32 v57, v59, v0
	global_store_dwordx4 v[60:61], v[54:57], off offset:3072
	s_cbranch_scc1 .LBB0_425
; __device__ __forceinline__ float bflo(unsigned w) { return __uint_as_float(w << 16); }
; __device__ __forceinline__ float bfhi(unsigned w) { return __uint_as_float(w & 0xffff0000u); }
; __device__ __forceinline__ void ln_panel_b(bf16_t* hb, float* outf, const float* gam, const float* bet) {
;     ...
;     for (int it = 0; it < 32 / NB; ++it) {
;         const int r = r0 + it * NB;
;         float v[NB][16];
; #pragma unroll
;         for (int b = 0; b < NB; ++b)
; #pragma unroll
;             for (int j = 0; j < 2; ++j)
; #pragma unroll
;                 for (int k = 0; k < 4; ++k) { v[b][8 * j + 2 * k] = bflo(nxt[b][j][k]); v[b][8 * j + 2 * k + 1] = bfhi(nxt[b][j][k]); }
;         if (it + 1 < 32 / NB) {
; #pragma unroll
;             for (int b = 0; b < NB; ++b)
; #pragma unroll
;                 for (int j = 0; j < 2; ++j) nxt[b][j] = ((const u32x4*)(hb + (size_t)(r + NB + b) * DM))[lane + 64 * j];
;         }
;         float s[NB], s2[NB];
; #pragma unroll
;         for (int b = 0; b < NB; ++b) { s[b] = 0.f;
; #pragma unroll
;             for (int k = 0; k < 16; ++k) s[b] += v[b][k]; }
; #pragma unroll
;         for (int o = 1; o < 64; o <<= 1)
; #pragma unroll
;             for (int b = 0; b < NB; ++b) s[b] += __shfl_xor(s[b], o);
; #pragma unroll
;         for (int b = 0; b < NB; ++b) { const float mean = s[b] * (1.f / DM); s2[b] = 0.f;
; #pragma unroll
;             for (int k = 0; k < 16; ++k) { v[b][k] -= mean; s2[b] += v[b][k] * v[b][k]; } }
; #pragma unroll
;         for (int o = 1; o < 64; o <<= 1)
; #pragma unroll
;             for (int b = 0; b < NB; ++b) s2[b] += __shfl_xor(s2[b], o);
	s_waitcnt vmcnt(7)
	v_and_b32_e32 v65, 0xffff0000, v34
	v_lshlrev_b32_e32 v34, 16, v34
	v_add_f32_e32 v66, 0, v34
	v_and_b32_e32 v64, 0xffff0000, v35
	v_lshlrev_b32_e32 v35, 16, v35
	v_add_f32_e32 v66, v66, v65
	v_add_f32_e32 v66, v66, v35
	v_and_b32_e32 v63, 0xffff0000, v36
	v_lshlrev_b32_e32 v36, 16, v36
	v_add_f32_e32 v66, v66, v64
	s_waitcnt vmcnt(5)
	v_and_b32_e32 v57, 0xffff0000, v42
	v_lshlrev_b32_e32 v42, 16, v42
	v_add_f32_e32 v66, v66, v36
	v_and_b32_e32 v62, 0xffff0000, v37
	v_lshlrev_b32_e32 v37, 16, v37
	v_add_f32_e32 v66, v66, v63
	v_add_f32_e32 v67, 0, v42
	v_and_b32_e32 v56, 0xffff0000, v43
	v_lshlrev_b32_e32 v43, 16, v43
	v_add_f32_e32 v66, v66, v37
	v_add_f32_e32 v67, v67, v57
	v_and_b32_e32 v61, 0xffff0000, v38
	v_lshlrev_b32_e32 v38, 16, v38
	v_add_f32_e32 v66, v66, v62
	v_add_f32_e32 v67, v67, v43
	v_and_b32_e32 v55, 0xffff0000, v44
	v_lshlrev_b32_e32 v44, 16, v44
	v_add_f32_e32 v66, v66, v38
	v_add_f32_e32 v67, v67, v56
	v_and_b32_e32 v60, 0xffff0000, v39
	v_lshlrev_b32_e32 v39, 16, v39
	v_add_f32_e32 v66, v66, v61
	v_add_f32_e32 v67, v67, v44
	v_and_b32_e32 v54, 0xffff0000, v45
	v_lshlrev_b32_e32 v45, 16, v45
	v_add_f32_e32 v66, v66, v39
	v_add_f32_e32 v67, v67, v55
	v_and_b32_e32 v59, 0xffff0000, v40
	v_lshlrev_b32_e32 v40, 16, v40
	v_add_f32_e32 v66, v66, v60
	v_add_f32_e32 v67, v67, v45
	s_waitcnt vmcnt(4)
	v_and_b32_e32 v53, 0xffff0000, v46
	v_lshlrev_b32_e32 v46, 16, v46
	v_add_f32_e32 v66, v66, v40
	v_add_f32_e32 v67, v67, v54
	v_and_b32_e32 v58, 0xffff0000, v41
	v_lshlrev_b32_e32 v41, 16, v41
	v_add_f32_e32 v66, v66, v59
	v_add_f32_e32 v67, v67, v46
	v_and_b32_e32 v52, 0xffff0000, v47
	v_lshlrev_b32_e32 v47, 16, v47
	v_add_f32_e32 v66, v66, v41
	v_add_f32_e32 v67, v67, v53
	v_add_f32_e32 v66, v66, v58
	v_add_f32_e32 v67, v67, v47
	v_and_b32_e32 v51, 0xffff0000, v48
	v_lshlrev_b32_e32 v48, 16, v48
	v_add_f32_e32 v67, v67, v52
	v_add_f32_e32 v67, v67, v48
	v_and_b32_e32 v0, 0xffff0000, v49
	v_lshlrev_b32_e32 v49, 16, v49
	v_add_f32_e32 v67, v67, v51
	v_add_f32_e32 v67, v67, v49
	v_add_f32_e32 v67, v67, v0
	s_waitcnt lgkmcnt(0)
	s_nop 1
	v_add_f32_dpp v66, v66, v66 quad_perm:[1,0,3,2] row_mask:0xf bank_mask:0xf
	s_or_b32 s10, s10, 30
	s_ashr_i32 s11, s10, 31
	v_lshlrev_b32_e32 v50, 4, v50
	s_movk_i32 s42, 0x400
	s_waitcnt lgkmcnt(0)
	s_nop 1
	v_add_f32_dpp v67, v67, v67 quad_perm:[1,0,3,2] row_mask:0xf bank_mask:0xf
	v_mov_b32_e32 v131, v1
	v_mov_b32_e32 v135, v1
	v_mov_b32_e32 v133, v1
	s_waitcnt lgkmcnt(0)
	s_nop 1
	v_add_f32_dpp v66, v66, v66 quad_perm:[2,3,0,1] row_mask:0xf bank_mask:0xf
	s_waitcnt lgkmcnt(0)
	s_nop 1
	v_add_f32_dpp v67, v67, v67 quad_perm:[2,3,0,1] row_mask:0xf bank_mask:0xf
	s_waitcnt lgkmcnt(0)
	s_nop 1
	v_add_f32_dpp v66, v66, v66 row_half_mirror row_mask:0xf bank_mask:0xf
	s_waitcnt lgkmcnt(0)
	s_nop 1
	v_add_f32_dpp v67, v67, v67 row_half_mirror row_mask:0xf bank_mask:0xf
	s_waitcnt lgkmcnt(0)
	s_nop 1
	v_add_f32_dpp v66, v66, v66 row_mirror row_mask:0xf bank_mask:0xf
	s_waitcnt lgkmcnt(0)
	s_nop 1
	v_add_f32_dpp v67, v67, v67 row_mirror row_mask:0xf bank_mask:0xf
	s_waitcnt lgkmcnt(0)
	s_waitcnt lgkmcnt(0)
	s_waitcnt lgkmcnt(0)
	s_nop 0
	v_readlane_b32 s98, v66, 0
	v_readlane_b32 s99, v66, 16
	v_readlane_b32 s100, v66, 32
	v_readlane_b32 s101, v66, 48
	v_mov_b32_e32 v66, s98
	v_add_f32_e32 v66, s99, v66
	v_mov_b32_e32 v68, s100
	v_add_f32_e32 v68, s101, v68
	v_add_f32_e32 v66, v66, v68
	v_fmac_f32_e32 v65, 0xba800000, v66
	v_fmac_f32_e32 v34, 0xba800000, v66
	v_fmac_f32_e32 v35, 0xba800000, v66
	v_fmac_f32_e32 v64, 0xba800000, v66
	s_waitcnt lgkmcnt(0)
	s_nop 0
	v_readlane_b32 s98, v67, 0
	v_readlane_b32 s99, v67, 16
	v_readlane_b32 s100, v67, 32
	v_readlane_b32 s101, v67, 48
	v_mov_b32_e32 v67, s98
	v_add_f32_e32 v67, s99, v67
	v_mov_b32_e32 v68, s100
	v_add_f32_e32 v68, s101, v68
	v_add_f32_e32 v67, v67, v68
	v_mul_f32_e32 v68, v65, v65
	v_fmac_f32_e32 v68, v34, v34
	v_fmac_f32_e32 v68, v35, v35
	v_fmac_f32_e32 v68, v64, v64
	v_fmac_f32_e32 v36, 0xba800000, v66
	v_fmac_f32_e32 v68, v36, v36
	v_fmac_f32_e32 v63, 0xba800000, v66
	v_fmac_f32_e32 v57, 0xba800000, v67
	v_fmac_f32_e32 v68, v63, v63
	v_fmac_f32_e32 v37, 0xba800000, v66
	v_fmac_f32_e32 v62, 0xba800000, v66
	v_fmac_f32_e32 v38, 0xba800000, v66
	v_fmac_f32_e32 v61, 0xba800000, v66
	v_fmac_f32_e32 v39, 0xba800000, v66
	v_fmac_f32_e32 v60, 0xba800000, v66
	v_fmac_f32_e32 v40, 0xba800000, v66
	v_fmac_f32_e32 v59, 0xba800000, v66
	v_fmac_f32_e32 v41, 0xba800000, v66
	v_fmac_f32_e32 v58, 0xba800000, v66
	v_fmac_f32_e32 v42, 0xba800000, v67
	v_mul_f32_e32 v66, v57, v57
	v_fmac_f32_e32 v68, v37, v37
	v_fmac_f32_e32 v66, v42, v42
	v_fmac_f32_e32 v43, 0xba800000, v67
	v_fmac_f32_e32 v68, v62, v62
	v_fmac_f32_e32 v66, v43, v43
	v_fmac_f32_e32 v56, 0xba800000, v67
	v_fmac_f32_e32 v68, v38, v38
	v_fmac_f32_e32 v66, v56, v56
	v_fmac_f32_e32 v44, 0xba800000, v67
	v_fmac_f32_e32 v68, v61, v61
	v_fmac_f32_e32 v66, v44, v44
	v_fmac_f32_e32 v55, 0xba800000, v67
	v_fmac_f32_e32 v68, v39, v39
	v_fmac_f32_e32 v66, v55, v55
	v_fmac_f32_e32 v45, 0xba800000, v67
	v_fmac_f32_e32 v68, v60, v60
	v_fmac_f32_e32 v66, v45, v45
	v_fmac_f32_e32 v54, 0xba800000, v67
	v_fmac_f32_e32 v68, v40, v40
	v_fmac_f32_e32 v66, v54, v54
	v_fmac_f32_e32 v46, 0xba800000, v67
	v_fmac_f32_e32 v68, v59, v59
	v_fmac_f32_e32 v66, v46, v46
	v_fmac_f32_e32 v53, 0xba800000, v67
	v_fmac_f32_e32 v68, v41, v41
	v_fmac_f32_e32 v66, v53, v53
	v_fmac_f32_e32 v47, 0xba800000, v67
	v_fmac_f32_e32 v68, v58, v58
	v_fmac_f32_e32 v66, v47, v47
	v_fmac_f32_e32 v52, 0xba800000, v67
	v_fmac_f32_e32 v66, v52, v52
	v_fmac_f32_e32 v48, 0xba800000, v67
	v_fmac_f32_e32 v51, 0xba800000, v67
	v_fmac_f32_e32 v49, 0xba800000, v67
	v_fmac_f32_e32 v0, 0xba800000, v67
	v_fmac_f32_e32 v66, v48, v48
	v_fmac_f32_e32 v66, v51, v51
	v_fmac_f32_e32 v66, v49, v49
	v_fmac_f32_e32 v66, v0, v0
	s_waitcnt lgkmcnt(0)
; __device__ __forceinline__ unsigned pk2(float lo, float hi) { unsigned r; asm("v_cvt_pk_bf16_f32 %0, %1, %2" : "=v"(r) : "v"(lo), "v"(hi)); return r; }
; __device__ __forceinline__ void block_fence() { __builtin_amdgcn_fence(__ATOMIC_RELEASE, "workgroup"); __syncthreads(); __builtin_amdgcn_fence(__ATOMIC_ACQUIRE, "workgroup"); }
; __device__ __forceinline__ void ln_panel_b(bf16_t* hb, float* outf, const float* gam, const float* bet) {
;     ...
;         for (int o = 1; o < 64; o <<= 1)
; #pragma unroll
;             for (int b = 0; b < NB; ++b) s2[b] += __shfl_xor(s2[b], o);
; #pragma unroll
;         for (int b = 0; b < NB; ++b) {
;             const float rstd = 1.f / sqrtf(s2[b] * (1.f / DM) + LN_EPS);
; #pragma unroll
;             for (int j = 0; j < 2; ++j) {
;                 float o[8];
; #pragma unroll
;                 for (int k = 0; k < 8; ++k) o[k] = v[b][8 * j + k] * rstd * gv[j][k >> 2][k & 3] + bv[j][k >> 2][k & 3];
;                 if (outf) { f32x4* op = (f32x4*)(outf + (size_t)(r + b) * DM + 512 * j + 8 * lane); op[0] = (f32x4){o[0], o[1], o[2], o[3]}; op[1] = (f32x4){o[4], o[5], o[6], o[7]}; }
;                 else { u32x4 w; w.x = pk2(o[0], o[1]); w.y = pk2(o[2], o[3]); w.z = pk2(o[4], o[5]); w.w = pk2(o[6], o[7]); ((u32x4*)(hb + (size_t)(r + b) * DM))[lane + 64 * j] = w; }
;             }
; __global__ void __launch_bounds__(512, 2) fwd_megakernel(Args a) {
;     ...
;         block_fence();
	s_nop 1
	v_add_f32_dpp v67, v68, v68 quad_perm:[1,0,3,2] row_mask:0xf bank_mask:0xf
	s_waitcnt lgkmcnt(0)
	s_nop 1
	v_add_f32_dpp v66, v66, v66 quad_perm:[1,0,3,2] row_mask:0xf bank_mask:0xf
	s_waitcnt lgkmcnt(0)
	s_nop 1
	v_add_f32_dpp v67, v67, v67 quad_perm:[2,3,0,1] row_mask:0xf bank_mask:0xf
	s_waitcnt lgkmcnt(0)
	s_nop 1
	v_add_f32_dpp v66, v66, v66 quad_perm:[2,3,0,1] row_mask:0xf bank_mask:0xf
	s_waitcnt lgkmcnt(0)
	s_nop 1
	v_add_f32_dpp v67, v67, v67 row_half_mirror row_mask:0xf bank_mask:0xf
	s_waitcnt lgkmcnt(0)
	s_nop 1
	v_add_f32_dpp v66, v66, v66 row_half_mirror row_mask:0xf bank_mask:0xf
	s_waitcnt lgkmcnt(0)
	s_nop 1
	v_add_f32_dpp v67, v67, v67 row_mirror row_mask:0xf bank_mask:0xf
	s_waitcnt lgkmcnt(0)
	s_nop 1
	v_add_f32_dpp v66, v66, v66 row_mirror row_mask:0xf bank_mask:0xf
	s_waitcnt lgkmcnt(0)
	s_waitcnt lgkmcnt(0)
	s_waitcnt lgkmcnt(0)
	s_nop 0
	v_readlane_b32 s98, v67, 0
	v_readlane_b32 s99, v67, 16
	v_readlane_b32 s100, v67, 32
	v_readlane_b32 s101, v67, 48
	v_mov_b32_e32 v67, s98
	v_add_f32_e32 v67, s99, v67
	v_mov_b32_e32 v68, s100
	v_add_f32_e32 v68, s101, v68
	v_add_f32_e32 v67, v67, v68
	v_fmamk_f32 v67, v67, 0x3a800000, v231
	v_cmp_gt_f32_e32 vcc, s97, v67
	s_waitcnt lgkmcnt(0)
	s_nop 0
	v_readlane_b32 s98, v66, 0
	v_readlane_b32 s99, v66, 16
	v_readlane_b32 s100, v66, 32
	v_readlane_b32 s101, v66, 48
	v_mov_b32_e32 v66, s98
	v_add_f32_e32 v66, s99, v66
	v_mov_b32_e32 v68, s100
	v_add_f32_e32 v68, s101, v68
	v_add_f32_e32 v66, v66, v68
	v_mul_f32_e32 v68, 0x4f800000, v67
	v_cndmask_b32_e32 v67, v67, v68, vcc
	v_sqrt_f32_e32 v68, v67
	s_nop 0
	v_add_u32_e32 v69, -1, v68
	v_fma_f32 v70, -v69, v68, v67
	v_cmp_ge_f32_e64 s[2:3], 0, v70
	v_add_u32_e32 v70, 1, v68
	s_nop 0
	v_cndmask_b32_e64 v69, v68, v69, s[2:3]
	v_fma_f32 v68, -v70, v68, v67
	v_cmp_lt_f32_e64 s[2:3], 0, v68
	s_nop 1
	v_cndmask_b32_e64 v68, v69, v70, s[2:3]
	v_mul_f32_e32 v69, 0x37800000, v68
	v_cndmask_b32_e32 v68, v68, v69, vcc
	v_cmp_class_f32_e32 vcc, v67, v232
	s_nop 1
	v_cndmask_b32_e32 v67, v68, v67, vcc
	v_div_scale_f32 v68, s[2:3], v67, v67, 1.0
	v_rcp_f32_e32 v69, v68
	s_lshl_b64 s[2:3], s[10:11], 11
	s_add_u32 s2, s4, s2
	s_addc_u32 s3, s5, s3
	v_fma_f32 v70, -v68, v69, 1.0
	v_fmac_f32_e32 v69, v70, v69
	v_div_scale_f32 v70, vcc, 1.0, v67, 1.0
	v_mul_f32_e32 v71, v70, v69
	v_fma_f32 v72, -v68, v71, v70
	v_fmac_f32_e32 v71, v72, v69
	v_fma_f32 v68, -v68, v71, v70
	v_div_fmas_f32 v68, v68, v69, v71
	v_div_fixup_f32 v67, v68, v67, 1.0
	v_mul_f32_e32 v34, v34, v67
	v_fma_f32 v34, v30, v34, v22
	v_mul_f32_e32 v65, v65, v67
	v_mul_f32_e32 v35, v35, v67
	v_mul_f32_e32 v36, v36, v67
	v_mul_f32_e32 v37, v37, v67
	v_fma_f32 v65, v31, v65, v23
	v_fma_f32 v35, v32, v35, v24
	v_mul_f32_e32 v64, v64, v67
	v_fma_f32 v36, v26, v36, v18
	v_mul_f32_e32 v63, v63, v67
	v_fma_f32 v37, v28, v37, v20
	v_mul_f32_e32 v62, v62, v67
	v_cvt_pk_bf16_f32 v34, v34, v65
	v_fma_f32 v64, v33, v64, v25
	v_fma_f32 v63, v27, v63, v19
	v_fma_f32 v62, v29, v62, v21
	v_cvt_pk_bf16_f32 v35, v35, v64
	v_cvt_pk_bf16_f32 v36, v36, v63
	v_cvt_pk_bf16_f32 v37, v37, v62
	global_store_dwordx4 v50, v[34:37], s[2:3]
	s_nop 1
	v_mul_f32_e32 v34, v38, v67
	v_fma_f32 v34, v14, v34, v6
	v_mul_f32_e32 v35, v61, v67
	v_mul_f32_e32 v36, v39, v67
	v_mul_f32_e32 v37, v60, v67
	v_fma_f32 v35, v15, v35, v7
	v_fma_f32 v36, v16, v36, v8
	v_fma_f32 v37, v17, v37, v9
	v_mul_f32_e32 v38, v40, v67
	v_mul_f32_e32 v39, v59, v67
	v_mul_f32_e32 v40, v41, v67
	v_mul_f32_e32 v41, v58, v67
	v_cvt_pk_bf16_f32 v34, v34, v35
	v_fma_f32 v38, v10, v38, v2
	v_fma_f32 v39, v11, v39, v3
	v_fma_f32 v40, v12, v40, v4
	v_fma_f32 v41, v13, v41, v5
	v_cvt_pk_bf16_f32 v35, v36, v37
	v_cvt_pk_bf16_f32 v36, v38, v39
	v_cvt_pk_bf16_f32 v37, v40, v41
	global_store_dwordx4 v50, v[34:37], s[2:3] offset:1024
	s_nop 1
	v_fmamk_f32 v34, v66, 0x3a800000, v231
	v_cmp_gt_f32_e32 vcc, s97, v34
	v_mul_f32_e32 v35, 0x4f800000, v34
	s_nop 0
	v_cndmask_b32_e32 v34, v34, v35, vcc
	v_sqrt_f32_e32 v35, v34
	s_nop 0
	v_add_u32_e32 v36, -1, v35
	v_fma_f32 v37, -v36, v35, v34
	v_cmp_ge_f32_e64 s[2:3], 0, v37
	v_add_u32_e32 v37, 1, v35
	s_nop 0
	v_cndmask_b32_e64 v36, v35, v36, s[2:3]
	v_fma_f32 v35, -v37, v35, v34
	v_cmp_lt_f32_e64 s[2:3], 0, v35
	s_nop 1
	v_cndmask_b32_e64 v35, v36, v37, s[2:3]
	v_mul_f32_e32 v36, 0x37800000, v35
	v_cndmask_b32_e32 v35, v35, v36, vcc
	v_cmp_class_f32_e32 vcc, v34, v232
	s_nop 1
	v_cndmask_b32_e32 v34, v35, v34, vcc
	v_div_scale_f32 v35, s[2:3], v34, v34, 1.0
	v_rcp_f32_e32 v36, v35
	s_or_b32 s2, s8, 31
	s_ashr_i32 s3, s2, 31
	s_lshl_b64 s[2:3], s[2:3], 11
	v_fma_f32 v37, -v35, v36, 1.0
	v_fmac_f32_e32 v36, v37, v36
	v_div_scale_f32 v37, vcc, 1.0, v34, 1.0
	v_mul_f32_e32 v38, v37, v36
	v_fma_f32 v39, -v35, v38, v37
	v_fmac_f32_e32 v38, v39, v36
	v_fma_f32 v35, -v35, v38, v37
	v_div_fmas_f32 v35, v35, v36, v38
	v_div_fixup_f32 v34, v35, v34, 1.0
	v_mul_f32_e32 v35, v42, v34
	v_fma_f32 v22, v30, v35, v22
	v_mul_f32_e32 v30, v57, v34
	v_fma_f32 v23, v31, v30, v23
	v_mul_f32_e32 v30, v43, v34
	v_fma_f32 v24, v32, v30, v24
	v_mul_f32_e32 v30, v56, v34
	v_fmac_f32_e32 v25, v33, v30
	v_mul_f32_e32 v30, v44, v34
	v_fma_f32 v26, v26, v30, v18
	v_mul_f32_e32 v18, v55, v34
	v_fma_f32 v27, v27, v18, v19
	v_mul_f32_e32 v18, v45, v34
	s_add_u32 s2, s4, s2
	v_fma_f32 v28, v28, v18, v20
	v_mul_f32_e32 v18, v54, v34
	s_addc_u32 s3, s5, s3
	v_fmac_f32_e32 v21, v29, v18
	v_cvt_pk_bf16_f32 v18, v22, v23
	v_cvt_pk_bf16_f32 v19, v24, v25
	v_cvt_pk_bf16_f32 v20, v26, v27
	v_cvt_pk_bf16_f32 v21, v28, v21
	global_store_dwordx4 v50, v[18:21], s[2:3]
	v_mul_f32_e32 v0, v0, v34
	v_fmac_f32_e32 v5, v13, v0
	v_mul_f32_e32 v18, v46, v34
	v_fma_f32 v6, v14, v18, v6
	v_mul_f32_e32 v14, v53, v34
	v_fma_f32 v7, v15, v14, v7
	v_mul_f32_e32 v14, v47, v34
	v_fma_f32 v8, v16, v14, v8
	v_mul_f32_e32 v14, v52, v34
	v_fmac_f32_e32 v9, v17, v14
	v_mul_f32_e32 v14, v48, v34
	v_fma_f32 v10, v10, v14, v2
	v_mul_f32_e32 v2, v51, v34
	v_fma_f32 v11, v11, v2, v3
	v_mul_f32_e32 v2, v49, v34
	v_fma_f32 v12, v12, v2, v4
	v_cvt_pk_bf16_f32 v2, v6, v7
	v_cvt_pk_bf16_f32 v3, v8, v9
	v_cvt_pk_bf16_f32 v4, v10, v11
	v_cvt_pk_bf16_f32 v5, v12, v5
	global_store_dwordx4 v50, v[2:5], s[2:3] offset:1024
	v_readlane_b32 s2, v249, 0
	v_readlane_b32 s3, v249, 1
	v_mov_b32_e32 v15, v189
	s_waitcnt vmcnt(0)
	s_barrier
	v_readfirstlane_b32 s98, v189
	s_nop 3
	s_cmp_ge_u32 s98, 64
	s_cbranch_scc1 .Lgrp_bar0_done
	s_lshr_b32 s98, s88, 21
	s_and_b32 s99, s98, 7
	s_lshr_b32 s98, s98, 5
	s_lshl_b32 s98, s98, 3
	s_or_b32 s98, s98, s99
	s_lshl_b32 s98, s98, 5
	v_readlane_b32 s99, v248, 36
	s_nop 3
	s_lshl_b32 s99, s99, 4
	s_add_u32 s98, s98, s99
	s_add_u32 s98, s98, 14336
	v_mov_b32_e32 v2, s98
	v_mov_b32_e32 v3, 1
	s_mov_b64 s[100:101], exec
	s_mov_b64 exec, 1
	v_readlane_b32 s99, v248, 62
	s_nop 3
	s_cmp_eq_u32 s99, 1
	s_cbranch_scc1 .Lgrp_bar0_nowb
	buffer_wbl2 sc1

; #define PHASE_PTRS() CArgs* ka = kargs(); unsigned char* ws = ka->ws; unsigned char* PB = ws + WS_PANEL + (size_t)panel * PANEL_BYTES; \
;         bf16_t* HBp = (bf16_t*)(ws + WS_HB) + (size_t)panel * 256 * DM; float* Hp = ka->out + (size_t)panel * 256 * DM; (void)PB; (void)HBp; (void)Hp
; __device__ __forceinline__ void ln_panel_b(bf16_t* hb, float* outf, const float* gam, const float* bet) {
;     int tid_ = threadIdx.x; asm volatile("" : "+v"(tid_));
;     const int lane = tid_ & 63, wave = __builtin_amdgcn_readfirstlane(tid_ >> 6);
;     constexpr int NB = 2;
;     u32x4 nxt[NB][2];
;     const int r0 = wave * 32;
; #pragma unroll
;     for (int b = 0; b < NB; ++b)
; #pragma unroll
;         for (int j = 0; j < 2; ++j) nxt[b][j] = ((const u32x4*)(hb + (size_t)(r0 + b) * DM))[lane + 64 * j];
;     f32x4 gv[2][2], bv[2][2];
; #pragma unroll
;     for (int j = 0; j < 2; ++j)
; #pragma unroll
;         for (int q = 0; q < 2; ++q) { gv[j][q] = *(const f32x4*)(gam + 512 * j + 8 * lane + 4 * q); bv[j][q] = *(const f32x4*)(bet + 512 * j + 8 * lane + 4 * q); }
; __global__ void __launch_bounds__(512, 2) fwd_megakernel(Args a) {
;     ...
;         { PHASE_PTRS(); ln_panel_b(HBp, (l + 1 == NLAYER) ? Hp : nullptr, ka->in[28] + l * DM, ka->in[29] + l * DM); }
.Lgrp_bar2_done:
	s_barrier
	s_load_dwordx8 s[40:47], s[2:3], 0xe0
	v_readlane_b32 s2, v249, 8
	v_readlane_b32 s3, v249, 9
	v_mov_b32_e32 v0, v189
	s_waitcnt lgkmcnt(0)
	s_add_u32 s1, s46, s2
	s_addc_u32 s2, s47, s3
	s_add_u32 s4, s1, 0x6000000
	s_addc_u32 s5, s2, 0
	v_readlane_b32 s2, v249, 4
	v_readlane_b32 s3, v249, 5
	s_lshl_b64 s[2:3], s[2:3], 2
	s_add_u32 s1, s44, s2
	s_addc_u32 s8, s45, s3
	v_readlane_b32 s2, v248, 32
	v_readlane_b32 s3, v248, 33
	s_and_b64 s[2:3], s[2:3], exec
	s_cselect_b32 s11, s8, 0
	s_cselect_b32 s10, s1, 0
	s_add_u32 s2, s40, s20
	s_addc_u32 s3, s41, s21
	s_add_u32 s8, s42, s20
	v_readfirstlane_b32 s1, v0
	s_addc_u32 s9, s43, s21
	s_ashr_i32 s36, s1, 1
	s_and_b32 s18, s36, 0xffffffe0
	s_ashr_i32 s19, s18, 31
	s_lshl_b64 s[38:39], s[18:19], 11
	v_and_b32_e32 v66, 63, v0
	s_add_u32 s20, s4, s38
	s_addc_u32 s21, s5, s39
	v_lshlrev_b32_e32 v0, 4, v66
	global_load_dwordx4 v[50:53], v0, s[20:21]
	global_load_dwordx4 v[62:65], v0, s[20:21] offset:1024
	s_or_b32 s20, s18, 1
	s_ashr_i32 s21, s20, 31
	s_lshl_b64 s[20:21], s[20:21], 11
	s_add_u32 s20, s4, s20
	s_addc_u32 s21, s5, s21
	v_lshlrev_b32_e32 v34, 5, v66
	global_load_dwordx4 v[54:57], v0, s[20:21]
	global_load_dwordx4 v[58:61], v0, s[20:21] offset:1024
	global_load_dwordx4 v[26:29], v34, s[2:3]
	global_load_dwordx4 v[18:21], v34, s[2:3] offset:16
	global_load_dwordx4 v[30:33], v34, s[8:9]
	global_load_dwordx4 v[22:25], v34, s[8:9] offset:16
	global_load_dwordx4 v[10:13], v34, s[2:3] offset:2048
	global_load_dwordx4 v[2:5], v34, s[2:3] offset:2064
	global_load_dwordx4 v[14:17], v34, s[8:9] offset:2048
	global_load_dwordx4 v[6:9], v34, s[8:9] offset:2064
	s_cmp_lg_u64 s[10:11], 0
	v_readlane_b32 s2, v249, 6
	s_cselect_b64 s[26:27], -1, 0
	v_readlane_b32 s3, v249, 7
	s_add_u32 s1, s46, s2
	s_addc_u32 s3, s47, s3
	s_add_u32 s2, s1, s38
	s_addc_u32 s3, s3, s39
	v_lshl_add_u64 v[70:71], s[2:3], 0, v[0:1]
	s_lshl_b64 s[2:3], s[18:19], 12
	s_add_u32 s2, s10, s2
	v_mov_b32_e32 v35, v1
	s_addc_u32 s3, s11, s3
	v_lshl_add_u64 v[34:35], s[2:3], 0, v[34:35]
	s_mov_b64 s[2:3], 0x1000
	v_lshlrev_b32_e32 v68, 3, v66
	s_mov_b64 s[20:21], 0
	v_lshl_add_u64 v[72:73], v[34:35], 0, s[2:3]
	s_waitcnt vmcnt(0)
	s_branch .LBB0_458
